# P1 128x128 tiles: half-stage LDS-DMA ring (exec-masked half fills, 3 half-stages in flight, wait+barrier per 32-wide K half)
# baseline (speedup 1.0000x reference)
; #define GLDS_STAGE(st, kt_) do { \
;         _Pragma("unroll") for (int i_ = 0; i_ < FI; ++i_) { \
;             glds16(ap + (size_t)(32 * i_) * lda + (kt_) * 64, l3a + (st) + tid * 16 + i_ * 4096); \
;             glds16(bp + (size_t)(32 * i_) * ldb + (kt_) * 64, l3a + (st) + OPB + tid * 16 + i_ * 4096); } } while (0)
; #define GLDS_STAGE(st, kt_) do { \
;         _Pragma("unroll") for (int i_ = 0; i_ < 4; ++i_) { \
;             glds16(ap + (size_t)(64 * i_) * lda + (kt_) * 64, l3a + (st) + tid * 16 + i_ * 8192); \
;             glds16(bp + (size_t)(64 * i_) * ldb + (kt_) * 64, l3a + (st) + 32768 + tid * 16 + i_ * 8192); } } while (0)
; template <int WT, class Epi>
; DEV void gemm_tile(const bf16_t* __restrict__ A, int lda, const bf16_t* __restrict__ Bt, int ldb, int K, unsigned char* lds, const Epi& epi) {
;     ...
;     constexpr int NSTG = 65536 / STB;
; #pragma unroll
;     for (int s_ = 0; s_ < NSTG - 1; ++s_) if (s_ < nk) GLDS_STAGE(s_ * STB, s_);
;     const int aoff = (wr * WT + fr) * 128, boff = OPB + (wc * WT + fr) * 128, sw = fr & 7;
;     int cur = 0, nxt = (NSTG - 1) * STB;
;     for (int kt = 0; kt < nk; ++kt) {
;         if (NSTG == 4 && kt + 2 < nk) { if (FI == 2) asm volatile("s_waitcnt vmcnt(8)" ::: "memory"); else asm volatile("s_waitcnt vmcnt(0)" ::: "memory"); }
;         else asm volatile("s_waitcnt vmcnt(0)" ::: "memory");
;         __syncthreads();
;         if (kt + NSTG - 1 < nk) GLDS_STAGE(nxt, kt + NSTG - 1);
; #pragma unroll
;         for (int kh = 0; kh < 2; ++kh) {
;             bf16x8 af[FI], bfr[FI];
;             const int ch = ((kh * 4 + fq) ^ sw) << 4;
; #pragma unroll
;             for (int i = 0; i < FI; ++i) { af[i] = *(const bf16x8*)(lds + cur + aoff + i * 2048 + ch); bfr[i] = *(const bf16x8*)(lds + cur + boff + i * 2048 + ch); }
; #pragma unroll
;             for (int mi = 0; mi < FI; ++mi)
; #pragma unroll
;                 for (int ni = 0; ni < FI; ++ni) acc[mi][ni] = __builtin_amdgcn_mfma_f32_16x16x32_bf16(bfr[ni], af[mi], acc[mi][ni], 0, 0, 0);
;         }
;         nxt = cur; cur += STB; if (cur == NSTG * STB) cur = 0;
;     }
.LBB0_184:
	s_mov_b32 s46, m0
	s_mov_b32 s42, 0
	s_mov_b32 s43, 0x8000
	v_add_u32_e32 v142, s43, v83
	v_lshl_add_u64 v[124:125], v[78:79], 0, s[4:5]
	v_lshl_add_u64 v[126:127], v[76:77], 0, s[4:5]
	v_readfirstlane_b32 s38, v142
	s_add_i32 s39, s38, 0x4000
	s_mov_b32 exec_lo, 0x0f0f0f0f
	s_mov_b32 exec_hi, 0xf0f0f0f0
	s_mov_b32 m0, s38
	v_lshl_add_u64 v[128:129], v[124:125], 0, s[30:31]
	global_load_lds_dwordx4 v[124:125], off
	s_mov_b32 m0, s39
	v_lshl_add_u64 v[140:141], v[126:127], 0, s[30:31]
	global_load_lds_dwordx4 v[126:127], off
	s_add_i32 s40, s38, 0x1000
	s_mov_b32 m0, s40
	s_add_i32 s40, s39, 0x1000
	global_load_lds_dwordx4 v[128:129], off
	s_mov_b32 m0, s40
	v_lshl_add_u64 v[128:129], v[124:125], 0, s[34:35]
	global_load_lds_dwordx4 v[140:141], off
	v_lshl_add_u64 v[140:141], v[126:127], 0, s[34:35]
	s_add_i32 s40, s38, 0x2000
	s_mov_b32 m0, s40
	s_add_i32 s40, s39, 0x2000
	global_load_lds_dwordx4 v[128:129], off
	s_mov_b32 m0, s40
	v_lshl_add_u64 v[128:129], v[124:125], 0, s[36:37]
	global_load_lds_dwordx4 v[140:141], off
	v_lshl_add_u64 v[140:141], v[126:127], 0, s[36:37]
	s_add_i32 s40, s38, 0x3000
	s_mov_b32 m0, s40
	s_add_i32 s40, s39, 0x3000
	global_load_lds_dwordx4 v[128:129], off
	s_mov_b32 m0, s40
	s_nop 0
	global_load_lds_dwordx4 v[140:141], off
	s_mov_b64 exec, -1
	s_waitcnt vmcnt(8)
.Lg128_0_loop:
	s_add_i32 s40, s53, s42
	s_xor_b32 s43, s42, 0x8000
	v_add_u32_e32 v122, s40, v82
	v_add_u32_e32 v123, s40, v85
	v_add_u32_e32 v122, v122, v84
	v_add_u32_e32 v123, v123, v84
	s_waitcnt vmcnt(16)
	s_barrier
	v_add_u32_e32 v142, s43, v83
	v_lshl_add_u64 v[124:125], v[78:79], 0, s[4:5]
	v_lshl_add_u64 v[126:127], v[76:77], 0, s[4:5]
	v_readfirstlane_b32 s38, v142
	s_add_i32 s39, s38, 0x4000
	s_mov_b32 exec_lo, 0xf0f0f0f0
	s_mov_b32 exec_hi, 0x0f0f0f0f
	s_mov_b32 m0, s38
	v_lshl_add_u64 v[128:129], v[124:125], 0, s[30:31]
	global_load_lds_dwordx4 v[124:125], off
	s_mov_b32 m0, s39
	v_lshl_add_u64 v[140:141], v[126:127], 0, s[30:31]
	global_load_lds_dwordx4 v[126:127], off
	s_add_i32 s40, s38, 0x1000
	s_mov_b32 m0, s40
	s_add_i32 s40, s39, 0x1000
	global_load_lds_dwordx4 v[128:129], off
	s_mov_b32 m0, s40
	v_lshl_add_u64 v[128:129], v[124:125], 0, s[34:35]
	global_load_lds_dwordx4 v[140:141], off
	v_lshl_add_u64 v[140:141], v[126:127], 0, s[34:35]
	s_add_i32 s40, s38, 0x2000
	s_mov_b32 m0, s40
	s_add_i32 s40, s39, 0x2000
	global_load_lds_dwordx4 v[128:129], off
	s_mov_b32 m0, s40
	v_lshl_add_u64 v[128:129], v[124:125], 0, s[36:37]
	global_load_lds_dwordx4 v[140:141], off
	v_lshl_add_u64 v[140:141], v[126:127], 0, s[36:37]
	s_add_i32 s40, s38, 0x3000
	s_mov_b32 m0, s40
	s_add_i32 s40, s39, 0x3000
	global_load_lds_dwordx4 v[128:129], off
	s_mov_b32 m0, s40
	s_nop 0
	global_load_lds_dwordx4 v[140:141], off
	s_mov_b64 exec, -1
	ds_read_b128 v[90:93], v123 offset:16384
	ds_read_b128 v[94:97], v123 offset:18432
	ds_read_b128 v[106:109], v122
	ds_read_b128 v[110:113], v122 offset:2048
	ds_read_b128 v[98:101], v123 offset:20480
	ds_read_b128 v[102:105], v123 offset:22528
	ds_read_b128 v[114:117], v122 offset:4096
	ds_read_b128 v[118:121], v122 offset:6144
	s_waitcnt lgkmcnt(5)
	v_mfma_f32_16x16x32_bf16 v[62:65], v[90:93], v[106:109], v[62:65]
	v_mfma_f32_16x16x32_bf16 v[54:57], v[94:97], v[106:109], v[54:57]
	s_waitcnt lgkmcnt(4)
	v_mfma_f32_16x16x32_bf16 v[38:41], v[90:93], v[110:113], v[38:41]
	v_mfma_f32_16x16x32_bf16 v[34:37], v[94:97], v[110:113], v[34:37]
	s_waitcnt lgkmcnt(2)
	v_mfma_f32_16x16x32_bf16 v[50:53], v[98:101], v[106:109], v[50:53]
	v_mfma_f32_16x16x32_bf16 v[46:49], v[102:105], v[106:109], v[46:49]
	v_mfma_f32_16x16x32_bf16 v[30:33], v[98:101], v[110:113], v[30:33]
	v_mfma_f32_16x16x32_bf16 v[26:29], v[102:105], v[110:113], v[26:29]
	s_waitcnt lgkmcnt(1)
	v_mfma_f32_16x16x32_bf16 v[22:25], v[90:93], v[114:117], v[22:25]
	v_mfma_f32_16x16x32_bf16 v[18:21], v[94:97], v[114:117], v[18:21]
	v_mfma_f32_16x16x32_bf16 v[14:17], v[98:101], v[114:117], v[14:17]
	v_mfma_f32_16x16x32_bf16 v[10:13], v[102:105], v[114:117], v[10:13]
	s_waitcnt lgkmcnt(0)
	v_mfma_f32_16x16x32_bf16 v[6:9], v[90:93], v[118:121], v[6:9]
	v_mfma_f32_16x16x32_bf16 v[2:5], v[94:97], v[118:121], v[2:5]
	v_mfma_f32_16x16x32_bf16 v[58:61], v[98:101], v[118:121], v[58:61]
	v_mfma_f32_16x16x32_bf16 v[42:45], v[102:105], v[118:121], v[42:45]
	s_add_i32 s40, s53, s42
	v_add_u32_e32 v122, s40, v82
	v_add_u32_e32 v123, s40, v85
	v_add_u32_e32 v122, v122, v81
	v_add_u32_e32 v123, v123, v81
	s_add_u32 s44, s4, 0x80
	s_addc_u32 s45, s5, 0
	s_waitcnt vmcnt(16)
	s_barrier
	s_cmp_eq_u32 s44, 0xf80
	s_cbranch_scc1 .Lg128_0_skip
	v_add_u32_e32 v142, s42, v83
	v_lshl_add_u64 v[124:125], v[78:79], 0, s[44:45]
	v_lshl_add_u64 v[126:127], v[76:77], 0, s[44:45]
	v_readfirstlane_b32 s38, v142
	s_add_i32 s39, s38, 0x4000
	s_mov_b32 exec_lo, 0x0f0f0f0f
	s_mov_b32 exec_hi, 0xf0f0f0f0
	s_mov_b32 m0, s38
	v_lshl_add_u64 v[128:129], v[124:125], 0, s[30:31]
	global_load_lds_dwordx4 v[124:125], off
	s_mov_b32 m0, s39
	v_lshl_add_u64 v[140:141], v[126:127], 0, s[30:31]
	global_load_lds_dwordx4 v[126:127], off
	s_add_i32 s40, s38, 0x1000
	s_mov_b32 m0, s40
	s_add_i32 s40, s39, 0x1000
	global_load_lds_dwordx4 v[128:129], off
	s_mov_b32 m0, s40
	v_lshl_add_u64 v[128:129], v[124:125], 0, s[34:35]
	global_load_lds_dwordx4 v[140:141], off
	v_lshl_add_u64 v[140:141], v[126:127], 0, s[34:35]
	s_add_i32 s40, s38, 0x2000
	s_mov_b32 m0, s40
	s_add_i32 s40, s39, 0x2000
	global_load_lds_dwordx4 v[128:129], off
	s_mov_b32 m0, s40
	v_lshl_add_u64 v[128:129], v[124:125], 0, s[36:37]
	global_load_lds_dwordx4 v[140:141], off
	v_lshl_add_u64 v[140:141], v[126:127], 0, s[36:37]
	s_add_i32 s40, s38, 0x3000
	s_mov_b32 m0, s40
	s_add_i32 s40, s39, 0x3000
	global_load_lds_dwordx4 v[128:129], off
	s_mov_b32 m0, s40
	s_nop 0
	global_load_lds_dwordx4 v[140:141], off
	s_mov_b64 exec, -1
; DEV bf16_t f2bf(float f) { return (bf16_t)(cvt_pk_bf16(f, 0.f) & 0xffffu); }
; DEV void store_bf4(bf16_t* p, f32x4 v) { uint2 w; w.x = cvt_pk_bf16(v[0], v[1]); w.y = cvt_pk_bf16(v[2], v[3]); *(uint2*)p = w; }
; #define GLDS_STAGE(st, kt_) do { \
;         _Pragma("unroll") for (int i_ = 0; i_ < FI; ++i_) { \
;             glds16(ap + (size_t)(32 * i_) * lda + (kt_) * 64, l3a + (st) + tid * 16 + i_ * 4096); \
;             glds16(bp + (size_t)(32 * i_) * ldb + (kt_) * 64, l3a + (st) + OPB + tid * 16 + i_ * 4096); } } while (0)
; template <int WT, class Epi>
; DEV void gemm_tile(const bf16_t* __restrict__ A, int lda, const bf16_t* __restrict__ Bt, int ldb, int K, unsigned char* lds, const Epi& epi) {
;     ...
;     for (int kt = 0; kt < nk; ++kt) {
;         if (NSTG == 4 && kt + 2 < nk) { if (FI == 2) asm volatile("s_waitcnt vmcnt(8)" ::: "memory"); else asm volatile("s_waitcnt vmcnt(0)" ::: "memory"); }
;         else asm volatile("s_waitcnt vmcnt(0)" ::: "memory");
;         __syncthreads();
;         if (kt + NSTG - 1 < nk) GLDS_STAGE(nxt, kt + NSTG - 1);
; #pragma unroll
;         for (int kh = 0; kh < 2; ++kh) {
;             bf16x8 af[FI], bfr[FI];
;             const int ch = ((kh * 4 + fq) ^ sw) << 4;
; #pragma unroll
;             for (int i = 0; i < FI; ++i) { af[i] = *(const bf16x8*)(lds + cur + aoff + i * 2048 + ch); bfr[i] = *(const bf16x8*)(lds + cur + boff + i * 2048 + ch); }
; #pragma unroll
;             for (int mi = 0; mi < FI; ++mi)
; #pragma unroll
;                 for (int ni = 0; ni < FI; ++ni) acc[mi][ni] = __builtin_amdgcn_mfma_f32_16x16x32_bf16(bfr[ni], af[mi], acc[mi][ni], 0, 0, 0);
;         }
;         nxt = cur; cur += STB; if (cur == NSTG * STB) cur = 0;
;     }
;     DEV void operator()(int r, int c, f32x4 v) const {
;         const int row = m0 + r, col = n0 + c;
;         if (col < D) {
;             __builtin_nontemporal_store(v, (f32x4*)(out + O_MK + (size_t)row * D + col));
;             store_bf4(mkb + (size_t)row * LDB + col, v);
;         } else {
;             const int cc = col - D, b = row >> 8, m = row & 255;
;             __builtin_nontemporal_store(v, (f32x4*)(out + O_MV + (size_t)row * D + cc));
;             bf16_t* p = mvt + ((size_t)b * D + cc) * LDM + m;
;             p[0] = f2bf(v[0]); p[LDM] = f2bf(v[1]); p[2 * LDM] = f2bf(v[2]); p[3 * LDM] = f2bf(v[3]);
;         }
.Lg128_0_skip:
	ds_read_b128 v[90:93], v123 offset:16384
	ds_read_b128 v[94:97], v123 offset:18432
	ds_read_b128 v[106:109], v122
	ds_read_b128 v[110:113], v122 offset:2048
	ds_read_b128 v[98:101], v123 offset:20480
	ds_read_b128 v[102:105], v123 offset:22528
	ds_read_b128 v[114:117], v122 offset:4096
	ds_read_b128 v[118:121], v122 offset:6144
	s_waitcnt lgkmcnt(5)
	v_mfma_f32_16x16x32_bf16 v[62:65], v[90:93], v[106:109], v[62:65]
	v_mfma_f32_16x16x32_bf16 v[54:57], v[94:97], v[106:109], v[54:57]
	s_waitcnt lgkmcnt(4)
	v_mfma_f32_16x16x32_bf16 v[38:41], v[90:93], v[110:113], v[38:41]
	v_mfma_f32_16x16x32_bf16 v[34:37], v[94:97], v[110:113], v[34:37]
	s_waitcnt lgkmcnt(2)
	v_mfma_f32_16x16x32_bf16 v[50:53], v[98:101], v[106:109], v[50:53]
	v_mfma_f32_16x16x32_bf16 v[46:49], v[102:105], v[106:109], v[46:49]
	v_mfma_f32_16x16x32_bf16 v[30:33], v[98:101], v[110:113], v[30:33]
	v_mfma_f32_16x16x32_bf16 v[26:29], v[102:105], v[110:113], v[26:29]
	s_waitcnt lgkmcnt(1)
	v_mfma_f32_16x16x32_bf16 v[22:25], v[90:93], v[114:117], v[22:25]
	v_mfma_f32_16x16x32_bf16 v[18:21], v[94:97], v[114:117], v[18:21]
	v_mfma_f32_16x16x32_bf16 v[14:17], v[98:101], v[114:117], v[14:17]
	v_mfma_f32_16x16x32_bf16 v[10:13], v[102:105], v[114:117], v[10:13]
	s_waitcnt lgkmcnt(0)
	v_mfma_f32_16x16x32_bf16 v[6:9], v[90:93], v[118:121], v[6:9]
	v_mfma_f32_16x16x32_bf16 v[2:5], v[94:97], v[118:121], v[2:5]
	v_mfma_f32_16x16x32_bf16 v[58:61], v[98:101], v[118:121], v[58:61]
	v_mfma_f32_16x16x32_bf16 v[42:45], v[102:105], v[118:121], v[42:45]
	s_mov_b64 s[4:5], s[44:45]
	s_xor_b32 s42, s42, 0x8000
	s_cmp_lg_u32 s4, 0xf80
	s_cbranch_scc1 .Lg128_0_loop
	s_mov_b32 m0, s46
	v_add_u32_e32 v102, s53, v85
	v_add_u32_e32 v103, s53, v82
	v_add_u32_e32 v98, v102, v84
	v_add_u32_e32 v104, v103, v84
	s_waitcnt vmcnt(0)
	s_barrier
	ds_read_b128 v[76:79], v98 offset:49152
	ds_read_b128 v[90:93], v98 offset:51200
	ds_read_b128 v[82:85], v104 offset:32768
	ds_read_b128 v[94:97], v98 offset:53248
	ds_read_b128 v[98:101], v98 offset:55296
	s_waitcnt lgkmcnt(2)
	v_mfma_f32_16x16x32_bf16 v[62:65], v[76:79], v[82:85], v[62:65]
	v_add_u32_e32 v102, v102, v81
	v_add_u32_e32 v81, v103, v81
	s_lshl_b32 s11, s8, 7
	v_mfma_f32_16x16x32_bf16 v[54:57], v[90:93], v[82:85], v[54:57]
	s_lshl_b32 s4, s7, 7
	s_cmpk_gt_u32 s6, 0x7f
	s_cselect_b64 s[6:7], -1, 0
	s_waitcnt lgkmcnt(1)
	v_mfma_f32_16x16x32_bf16 v[50:53], v[94:97], v[82:85], v[50:53]
	ds_read_b128 v[106:109], v81 offset:34816
	s_and_b64 vcc, exec, s[6:7]
	ds_read_b128 v[110:113], v81 offset:38912
	s_waitcnt lgkmcnt(2)
	v_mfma_f32_16x16x32_bf16 v[46:49], v[98:101], v[82:85], v[46:49]
	ds_read_b128 v[82:85], v104 offset:34816
	s_waitcnt lgkmcnt(0)
	v_mfma_f32_16x16x32_bf16 v[38:41], v[76:79], v[82:85], v[38:41]
	v_mfma_f32_16x16x32_bf16 v[34:37], v[90:93], v[82:85], v[34:37]
	v_mfma_f32_16x16x32_bf16 v[30:33], v[94:97], v[82:85], v[30:33]
	v_mfma_f32_16x16x32_bf16 v[26:29], v[98:101], v[82:85], v[26:29]
	ds_read_b128 v[82:85], v104 offset:36864
	s_waitcnt lgkmcnt(0)
	v_mfma_f32_16x16x32_bf16 v[22:25], v[76:79], v[82:85], v[22:25]
	v_mfma_f32_16x16x32_bf16 v[18:21], v[90:93], v[82:85], v[18:21]
	v_mfma_f32_16x16x32_bf16 v[14:17], v[94:97], v[82:85], v[14:17]
	v_mfma_f32_16x16x32_bf16 v[10:13], v[98:101], v[82:85], v[10:13]
	ds_read_b128 v[82:85], v104 offset:38912
	s_waitcnt lgkmcnt(0)
	v_mfma_f32_16x16x32_bf16 v[6:9], v[76:79], v[82:85], v[6:9]
	ds_read_b128 v[76:79], v102 offset:49152
	v_mfma_f32_16x16x32_bf16 v[2:5], v[90:93], v[82:85], v[2:5]
	v_mfma_f32_16x16x32_bf16 v[90:93], v[94:97], v[82:85], v[58:61]
	v_mfma_f32_16x16x32_bf16 v[94:97], v[98:101], v[82:85], v[42:45]
	ds_read_b128 v[82:85], v102 offset:51200
	ds_read_b128 v[98:101], v102 offset:53248
	ds_read_b128 v[102:105], v102 offset:55296
	ds_read_b128 v[42:45], v81 offset:32768
	s_waitcnt lgkmcnt(0)
	v_mfma_f32_16x16x32_bf16 v[62:65], v[76:79], v[42:45], v[62:65]
	v_mfma_f32_16x16x32_bf16 v[58:61], v[82:85], v[42:45], v[54:57]
	v_mfma_f32_16x16x32_bf16 v[54:57], v[98:101], v[42:45], v[50:53]
	v_mfma_f32_16x16x32_bf16 v[50:53], v[102:105], v[42:45], v[46:49]
	v_mfma_f32_16x16x32_bf16 v[46:49], v[76:79], v[106:109], v[38:41]
	v_mfma_f32_16x16x32_bf16 v[42:45], v[82:85], v[106:109], v[34:37]
	v_mfma_f32_16x16x32_bf16 v[38:41], v[98:101], v[106:109], v[30:33]
	v_mfma_f32_16x16x32_bf16 v[34:37], v[102:105], v[106:109], v[26:29]
	ds_read_b128 v[106:109], v81 offset:36864
	v_and_b32_e32 v81, 64, v80
	v_add_u32_e32 v80, s11, v89
	s_waitcnt lgkmcnt(0)
	v_mfma_f32_16x16x32_bf16 v[30:33], v[76:79], v[106:109], v[22:25]
	s_barrier
	v_mfma_f32_16x16x32_bf16 v[26:29], v[82:85], v[106:109], v[18:21]
	v_mfma_f32_16x16x32_bf16 v[22:25], v[98:101], v[106:109], v[14:17]
	s_nop 2
	v_lshlrev_b32_e32 v14, 2, v74
	v_mfma_f32_16x16x32_bf16 v[18:21], v[102:105], v[106:109], v[10:13]
	v_or3_b32 v74, v14, v81, s4
	s_mov_b64 s[4:5], -1
	v_ashrrev_i32_e32 v81, 31, v80
	v_mfma_f32_16x16x32_bf16 v[10:13], v[82:85], v[110:113], v[2:5]
	v_ashrrev_i32_e32 v84, 8, v80
	v_ashrrev_i32_e32 v85, 31, v84
	s_nop 0
	v_and_b32_e32 v2, 0xcf, v80
	v_mfma_f32_16x16x32_bf16 v[14:17], v[76:79], v[110:113], v[6:9]
	v_lshlrev_b32_e32 v82, 1, v2
	v_add_u32_e32 v78, 0xfffff800, v74
	v_mfma_f32_16x16x32_bf16 v[6:9], v[98:101], v[110:113], v[90:93]
	v_mfma_f32_16x16x32_bf16 v[2:5], v[102:105], v[110:113], v[94:97]
	s_cbranch_vccz .LBB0_187
	v_lshlrev_b64 v[76:77], 13, v[80:81]
	v_lshl_add_u64 v[76:77], s[18:19], 0, v[76:77]
	v_mov_b32_e32 v79, v75
	v_lshl_add_u64 v[76:77], v[78:79], 2, v[76:77]
	global_store_dwordx4 v[76:77], v[62:65], off nt
	v_lshlrev_b64 v[76:77], 11, v[84:85]
	v_lshl_add_u64 v[76:77], v[76:77], 0, v[78:79]
	v_mad_u64_u32 v[90:91], s[4:5], v76, s60, v[162:163]
	v_mad_i32_i24 v91, v77, s60, v91
	v_mov_b32_e32 v83, v75
	v_lshl_add_u64 v[76:77], v[90:91], 0, v[82:83]
	v_cvt_pk_bf16_f32 v79, v62, s0
	global_store_short v[76:77], v79, off
	v_cvt_pk_bf16_f32 v79, v63, s0
	global_store_short v[76:77], v79, off offset:576
	v_cvt_pk_bf16_f32 v79, v64, s0
	global_store_short v[76:77], v79, off offset:1152
	v_cvt_pk_bf16_f32 v79, v65, s0
	global_store_short v[76:77], v79, off offset:1728
	s_mov_b64 s[4:5], 0

; #define GLDS_STAGE(st, kt_) do { \
;         _Pragma("unroll") for (int i_ = 0; i_ < FI; ++i_) { \
;             glds16(ap + (size_t)(32 * i_) * lda + (kt_) * 64, l3a + (st) + tid * 16 + i_ * 4096); \
;             glds16(bp + (size_t)(32 * i_) * ldb + (kt_) * 64, l3a + (st) + OPB + tid * 16 + i_ * 4096); } } while (0)
; #define GLDS_STAGE(st, kt_) do { \
;         _Pragma("unroll") for (int i_ = 0; i_ < 4; ++i_) { \
;             glds16(ap + (size_t)(64 * i_) * lda + (kt_) * 64, l3a + (st) + tid * 16 + i_ * 8192); \
;             glds16(bp + (size_t)(64 * i_) * ldb + (kt_) * 64, l3a + (st) + 32768 + tid * 16 + i_ * 8192); } } while (0)
; template <int WT, class Epi>
; DEV void gemm_tile(const bf16_t* __restrict__ A, int lda, const bf16_t* __restrict__ Bt, int ldb, int K, unsigned char* lds, const Epi& epi) {
;     ...
;     constexpr int NSTG = 65536 / STB;
; #pragma unroll
;     for (int s_ = 0; s_ < NSTG - 1; ++s_) if (s_ < nk) GLDS_STAGE(s_ * STB, s_);
;     const int aoff = (wr * WT + fr) * 128, boff = OPB + (wc * WT + fr) * 128, sw = fr & 7;
;     int cur = 0, nxt = (NSTG - 1) * STB;
;     for (int kt = 0; kt < nk; ++kt) {
;         if (NSTG == 4 && kt + 2 < nk) { if (FI == 2) asm volatile("s_waitcnt vmcnt(8)" ::: "memory"); else asm volatile("s_waitcnt vmcnt(0)" ::: "memory"); }
;         else asm volatile("s_waitcnt vmcnt(0)" ::: "memory");
;         __syncthreads();
;         if (kt + NSTG - 1 < nk) GLDS_STAGE(nxt, kt + NSTG - 1);
; #pragma unroll
;         for (int kh = 0; kh < 2; ++kh) {
;             bf16x8 af[FI], bfr[FI];
;             const int ch = ((kh * 4 + fq) ^ sw) << 4;
; #pragma unroll
;             for (int i = 0; i < FI; ++i) { af[i] = *(const bf16x8*)(lds + cur + aoff + i * 2048 + ch); bfr[i] = *(const bf16x8*)(lds + cur + boff + i * 2048 + ch); }
; #pragma unroll
;             for (int mi = 0; mi < FI; ++mi)
; #pragma unroll
;                 for (int ni = 0; ni < FI; ++ni) acc[mi][ni] = __builtin_amdgcn_mfma_f32_16x16x32_bf16(bfr[ni], af[mi], acc[mi][ni], 0, 0, 0);
;         }
;         nxt = cur; cur += STB; if (cur == NSTG * STB) cur = 0;
;     }
.Lg128_1_loop:
	s_add_i32 s40, s53, s42
	s_xor_b32 s43, s42, 0x8000
	v_add_u32_e32 v122, s40, v84
	v_add_u32_e32 v123, s40, v89
	v_add_u32_e32 v122, v122, v85
	v_add_u32_e32 v123, v123, v85
	s_waitcnt vmcnt(16)
	s_barrier
	v_add_u32_e32 v142, s43, v83
	v_lshl_add_u64 v[124:125], v[78:79], 0, s[4:5]
	v_lshl_add_u64 v[126:127], v[76:77], 0, s[4:5]
	v_readfirstlane_b32 s38, v142
	s_add_i32 s39, s38, 0x4000
	s_mov_b32 exec_lo, 0xf0f0f0f0
	s_mov_b32 exec_hi, 0x0f0f0f0f
	s_mov_b32 m0, s38
	v_lshl_add_u64 v[128:129], v[124:125], 0, s[30:31]
	global_load_lds_dwordx4 v[124:125], off
	s_mov_b32 m0, s39
	v_lshl_add_u64 v[140:141], v[126:127], 0, s[30:31]
	global_load_lds_dwordx4 v[126:127], off
	s_add_i32 s40, s38, 0x1000
	s_mov_b32 m0, s40
	s_add_i32 s40, s39, 0x1000
	global_load_lds_dwordx4 v[128:129], off
	s_mov_b32 m0, s40
	v_lshl_add_u64 v[128:129], v[124:125], 0, s[34:35]
	global_load_lds_dwordx4 v[140:141], off
	v_lshl_add_u64 v[140:141], v[126:127], 0, s[34:35]
	s_add_i32 s40, s38, 0x2000
	s_mov_b32 m0, s40
	s_add_i32 s40, s39, 0x2000
	global_load_lds_dwordx4 v[128:129], off
	s_mov_b32 m0, s40
	v_lshl_add_u64 v[128:129], v[124:125], 0, s[36:37]
	global_load_lds_dwordx4 v[140:141], off
	v_lshl_add_u64 v[140:141], v[126:127], 0, s[36:37]
	s_add_i32 s40, s38, 0x3000
	s_mov_b32 m0, s40
	s_add_i32 s40, s39, 0x3000
	global_load_lds_dwordx4 v[128:129], off
	s_mov_b32 m0, s40
	s_nop 0
	global_load_lds_dwordx4 v[140:141], off
	s_mov_b64 exec, -1
	ds_read_b128 v[90:93], v123 offset:16384
	ds_read_b128 v[94:97], v123 offset:18432
	ds_read_b128 v[106:109], v122
	ds_read_b128 v[110:113], v122 offset:2048
	ds_read_b128 v[98:101], v123 offset:20480
	ds_read_b128 v[102:105], v123 offset:22528
	ds_read_b128 v[114:117], v122 offset:4096
	ds_read_b128 v[118:121], v122 offset:6144
	s_waitcnt lgkmcnt(5)
	v_mfma_f32_16x16x32_bf16 v[62:65], v[90:93], v[106:109], v[62:65]
	v_mfma_f32_16x16x32_bf16 v[54:57], v[94:97], v[106:109], v[54:57]
	s_waitcnt lgkmcnt(4)
	v_mfma_f32_16x16x32_bf16 v[38:41], v[90:93], v[110:113], v[38:41]
	v_mfma_f32_16x16x32_bf16 v[34:37], v[94:97], v[110:113], v[34:37]
	s_waitcnt lgkmcnt(2)
	v_mfma_f32_16x16x32_bf16 v[50:53], v[98:101], v[106:109], v[50:53]
	v_mfma_f32_16x16x32_bf16 v[46:49], v[102:105], v[106:109], v[46:49]
	v_mfma_f32_16x16x32_bf16 v[30:33], v[98:101], v[110:113], v[30:33]
	v_mfma_f32_16x16x32_bf16 v[26:29], v[102:105], v[110:113], v[26:29]
	s_waitcnt lgkmcnt(1)
	v_mfma_f32_16x16x32_bf16 v[22:25], v[90:93], v[114:117], v[22:25]
	v_mfma_f32_16x16x32_bf16 v[18:21], v[94:97], v[114:117], v[18:21]
	v_mfma_f32_16x16x32_bf16 v[14:17], v[98:101], v[114:117], v[14:17]
	v_mfma_f32_16x16x32_bf16 v[10:13], v[102:105], v[114:117], v[10:13]
	s_waitcnt lgkmcnt(0)
	v_mfma_f32_16x16x32_bf16 v[6:9], v[90:93], v[118:121], v[6:9]
	v_mfma_f32_16x16x32_bf16 v[2:5], v[94:97], v[118:121], v[2:5]
	v_mfma_f32_16x16x32_bf16 v[58:61], v[98:101], v[118:121], v[58:61]
	v_mfma_f32_16x16x32_bf16 v[42:45], v[102:105], v[118:121], v[42:45]
	s_add_i32 s40, s53, s42
	v_add_u32_e32 v122, s40, v84
	v_add_u32_e32 v123, s40, v89
	v_add_u32_e32 v122, v122, v82
	v_add_u32_e32 v123, v123, v82
	s_add_u32 s44, s4, 0x80
	s_addc_u32 s45, s5, 0
	s_waitcnt vmcnt(16)
	s_barrier
	s_cmp_eq_u32 s44, 0xf80
	s_cbranch_scc1 .Lg128_1_skip
	v_add_u32_e32 v142, s42, v83
	v_lshl_add_u64 v[124:125], v[78:79], 0, s[44:45]
	v_lshl_add_u64 v[126:127], v[76:77], 0, s[44:45]
	v_readfirstlane_b32 s38, v142
	s_add_i32 s39, s38, 0x4000
	s_mov_b32 exec_lo, 0x0f0f0f0f
	s_mov_b32 exec_hi, 0xf0f0f0f0
	s_mov_b32 m0, s38
	v_lshl_add_u64 v[128:129], v[124:125], 0, s[30:31]
	global_load_lds_dwordx4 v[124:125], off
	s_mov_b32 m0, s39
	v_lshl_add_u64 v[140:141], v[126:127], 0, s[30:31]
	global_load_lds_dwordx4 v[126:127], off
	s_add_i32 s40, s38, 0x1000
	s_mov_b32 m0, s40
	s_add_i32 s40, s39, 0x1000
	global_load_lds_dwordx4 v[128:129], off
	s_mov_b32 m0, s40
	v_lshl_add_u64 v[128:129], v[124:125], 0, s[34:35]
	global_load_lds_dwordx4 v[140:141], off
	v_lshl_add_u64 v[140:141], v[126:127], 0, s[34:35]
	s_add_i32 s40, s38, 0x2000
	s_mov_b32 m0, s40
	s_add_i32 s40, s39, 0x2000
	global_load_lds_dwordx4 v[128:129], off
	s_mov_b32 m0, s40
	v_lshl_add_u64 v[128:129], v[124:125], 0, s[36:37]
	global_load_lds_dwordx4 v[140:141], off
	v_lshl_add_u64 v[140:141], v[126:127], 0, s[36:37]
	s_add_i32 s40, s38, 0x3000
	s_mov_b32 m0, s40
	s_add_i32 s40, s39, 0x3000
	global_load_lds_dwordx4 v[128:129], off
	s_mov_b32 m0, s40
	s_nop 0
	global_load_lds_dwordx4 v[140:141], off
	s_mov_b64 exec, -1
; template <int WT, class Epi>
; DEV void gemm_tile(const bf16_t* __restrict__ A, int lda, const bf16_t* __restrict__ Bt, int ldb, int K, unsigned char* lds, const Epi& epi) {
;     ...
;     for (int kt = 0; kt < nk; ++kt) {
;         if (NSTG == 4 && kt + 2 < nk) { if (FI == 2) asm volatile("s_waitcnt vmcnt(8)" ::: "memory"); else asm volatile("s_waitcnt vmcnt(0)" ::: "memory"); }
;         else asm volatile("s_waitcnt vmcnt(0)" ::: "memory");
;         __syncthreads();
;         if (kt + NSTG - 1 < nk) GLDS_STAGE(nxt, kt + NSTG - 1);
; #pragma unroll
;         for (int kh = 0; kh < 2; ++kh) {
;             bf16x8 af[FI], bfr[FI];
;             const int ch = ((kh * 4 + fq) ^ sw) << 4;
; #pragma unroll
;             for (int i = 0; i < FI; ++i) { af[i] = *(const bf16x8*)(lds + cur + aoff + i * 2048 + ch); bfr[i] = *(const bf16x8*)(lds + cur + boff + i * 2048 + ch); }
; #pragma unroll
;             for (int mi = 0; mi < FI; ++mi)
; #pragma unroll
;                 for (int ni = 0; ni < FI; ++ni) acc[mi][ni] = __builtin_amdgcn_mfma_f32_16x16x32_bf16(bfr[ni], af[mi], acc[mi][ni], 0, 0, 0);
;         }
;         nxt = cur; cur += STB; if (cur == NSTG * STB) cur = 0;
;     }
;     DEV void operator()(int r, int c, f32x4 v) const {
;         const int row = m0 + r, col = n0 + c;
;         if (col < NPJ) {
;             store_bf4(proj + (size_t)row * NPJ + col, v);
;             const bool isconv = col < 3072, ispool = (col >= C_U && col < C_ZB);
;             if (isconv || ispool) {
;                 if (row < TP) {
;                     const int b = row >> 11, t = row & 2047;
;                     if (isconv) { if (t >= 2045) *(f32x4*)(out + O_CP + ((size_t)(b * 3 + (t - 2045))) * 3072 + col) = v; }
;                     else { if (t >= 2033) *(f32x4*)(out + O_PP + ((size_t)(b * 15 + (t - 2033))) * 1024 + (col - C_U)) = v; }
;                 } else {
;                     const int sb = (row - TP) >> 2, t = (row - TP) & 3;
;                     if (isconv) { if (t >= 1) *(f32x4*)(out + O_CS + ((size_t)(sb * 3 + (t - 1))) * 3072 + col) = v; }
;                     else *(f32x4*)(out + O_PS + ((size_t)(sb * 15 + 11 + t)) * 1024 + (col - C_U)) = v;
;                 }
;             }
;         } else if (col < NPJ + 16) {
;             *(f32x4*)(ab + (size_t)row * 16 + (col - NPJ)) = v;
;         }
.Lg128_1_skip:
	ds_read_b128 v[90:93], v123 offset:16384
	ds_read_b128 v[94:97], v123 offset:18432
	ds_read_b128 v[106:109], v122
	ds_read_b128 v[110:113], v122 offset:2048
	ds_read_b128 v[98:101], v123 offset:20480
	ds_read_b128 v[102:105], v123 offset:22528
	ds_read_b128 v[114:117], v122 offset:4096
	ds_read_b128 v[118:121], v122 offset:6144
	s_waitcnt lgkmcnt(5)
	v_mfma_f32_16x16x32_bf16 v[62:65], v[90:93], v[106:109], v[62:65]
	v_mfma_f32_16x16x32_bf16 v[54:57], v[94:97], v[106:109], v[54:57]
	s_waitcnt lgkmcnt(4)
	v_mfma_f32_16x16x32_bf16 v[38:41], v[90:93], v[110:113], v[38:41]
	v_mfma_f32_16x16x32_bf16 v[34:37], v[94:97], v[110:113], v[34:37]
	s_waitcnt lgkmcnt(2)
	v_mfma_f32_16x16x32_bf16 v[50:53], v[98:101], v[106:109], v[50:53]
	v_mfma_f32_16x16x32_bf16 v[46:49], v[102:105], v[106:109], v[46:49]
	v_mfma_f32_16x16x32_bf16 v[30:33], v[98:101], v[110:113], v[30:33]
	v_mfma_f32_16x16x32_bf16 v[26:29], v[102:105], v[110:113], v[26:29]
	s_waitcnt lgkmcnt(1)
	v_mfma_f32_16x16x32_bf16 v[22:25], v[90:93], v[114:117], v[22:25]
	v_mfma_f32_16x16x32_bf16 v[18:21], v[94:97], v[114:117], v[18:21]
	v_mfma_f32_16x16x32_bf16 v[14:17], v[98:101], v[114:117], v[14:17]
	v_mfma_f32_16x16x32_bf16 v[10:13], v[102:105], v[114:117], v[10:13]
	s_waitcnt lgkmcnt(0)
	v_mfma_f32_16x16x32_bf16 v[6:9], v[90:93], v[118:121], v[6:9]
	v_mfma_f32_16x16x32_bf16 v[2:5], v[94:97], v[118:121], v[2:5]
	v_mfma_f32_16x16x32_bf16 v[58:61], v[98:101], v[118:121], v[58:61]
	v_mfma_f32_16x16x32_bf16 v[42:45], v[102:105], v[118:121], v[42:45]
	s_mov_b64 s[4:5], s[44:45]
	s_xor_b32 s42, s42, 0x8000
	s_cmp_lg_u32 s4, 0xf80
	s_cbranch_scc1 .Lg128_1_loop
	s_mov_b32 m0, s46
	v_add_u32_e32 v83, s53, v89
	v_add_u32_e32 v89, v83, v85
	s_waitcnt vmcnt(0)
	s_barrier
	ds_read_b128 v[76:79], v89 offset:49152
	ds_read_b128 v[94:97], v89 offset:51200
	ds_read_b128 v[98:101], v89 offset:53248
	ds_read_b128 v[102:105], v89 offset:55296
	v_add_u32_e32 v84, s53, v84
	v_add_u32_e32 v85, v84, v85
	ds_read_b128 v[90:93], v85 offset:32768
	v_add_u32_e32 v89, v84, v82
	ds_read_b128 v[110:113], v89 offset:36864
	s_waitcnt lgkmcnt(1)
	v_mfma_f32_16x16x32_bf16 v[62:65], v[76:79], v[90:93], v[62:65]
	ds_read_b128 v[114:117], v89 offset:38912
	s_lshl_b32 s4, s6, 7
	s_and_b32 s26, s10, 0x7ffffe0
	v_mfma_f32_16x16x32_bf16 v[54:57], v[94:97], v[90:93], v[54:57]
	s_cmpk_lg_i32 s26, 0x80
	s_cselect_b64 s[44:45], -1, 0
	v_mfma_f32_16x16x32_bf16 v[50:53], v[98:101], v[90:93], v[50:53]
	v_mfma_f32_16x16x32_bf16 v[46:49], v[102:105], v[90:93], v[46:49]
	ds_read_b128 v[90:93], v85 offset:34816
	s_waitcnt lgkmcnt(0)
	v_mfma_f32_16x16x32_bf16 v[38:41], v[76:79], v[90:93], v[38:41]
	v_mfma_f32_16x16x32_bf16 v[34:37], v[94:97], v[90:93], v[34:37]
	v_mfma_f32_16x16x32_bf16 v[30:33], v[98:101], v[90:93], v[30:33]
	v_mfma_f32_16x16x32_bf16 v[26:29], v[102:105], v[90:93], v[26:29]
	ds_read_b128 v[90:93], v85 offset:36864
	s_waitcnt lgkmcnt(0)
	v_mfma_f32_16x16x32_bf16 v[22:25], v[76:79], v[90:93], v[22:25]
	v_mfma_f32_16x16x32_bf16 v[18:21], v[94:97], v[90:93], v[18:21]
	v_mfma_f32_16x16x32_bf16 v[14:17], v[98:101], v[90:93], v[14:17]
	v_mfma_f32_16x16x32_bf16 v[10:13], v[102:105], v[90:93], v[10:13]
	ds_read_b128 v[90:93], v85 offset:38912
	s_waitcnt lgkmcnt(0)
	v_mfma_f32_16x16x32_bf16 v[6:9], v[76:79], v[90:93], v[6:9]
	v_add_u32_e32 v76, v83, v82
	ds_read_b128 v[82:85], v76 offset:51200
	ds_read_b128 v[106:109], v76 offset:55296
	v_mfma_f32_16x16x32_bf16 v[2:5], v[94:97], v[90:93], v[2:5]
	v_mfma_f32_16x16x32_bf16 v[94:97], v[98:101], v[90:93], v[58:61]
	ds_read_b128 v[98:101], v76 offset:49152
	v_mfma_f32_16x16x32_bf16 v[90:93], v[102:105], v[90:93], v[42:45]
	ds_read_b128 v[102:105], v76 offset:53248
	ds_read_b128 v[76:79], v89 offset:34816
	s_nop 0
	ds_read_b128 v[42:45], v89 offset:32768
	s_waitcnt lgkmcnt(0)
	v_mfma_f32_16x16x32_bf16 v[62:65], v[98:101], v[42:45], v[62:65]
	s_barrier
	v_mfma_f32_16x16x32_bf16 v[58:61], v[82:85], v[42:45], v[54:57]
	v_mfma_f32_16x16x32_bf16 v[54:57], v[102:105], v[42:45], v[50:53]
	v_mfma_f32_16x16x32_bf16 v[50:53], v[106:109], v[42:45], v[46:49]
	v_mfma_f32_16x16x32_bf16 v[46:49], v[98:101], v[76:79], v[38:41]
	v_mfma_f32_16x16x32_bf16 v[42:45], v[82:85], v[76:79], v[34:37]
	v_mfma_f32_16x16x32_bf16 v[38:41], v[102:105], v[76:79], v[30:33]
	v_mfma_f32_16x16x32_bf16 v[34:37], v[106:109], v[76:79], v[26:29]
	v_and_b32_e32 v76, 64, v80
	v_mfma_f32_16x16x32_bf16 v[26:29], v[82:85], v[110:113], v[18:21]
	s_nop 2
	v_lshlrev_b32_e32 v18, 2, v74
	v_add_u32_e32 v74, s68, v81
	v_or3_b32 v76, v18, v76, s4
	v_mfma_f32_16x16x32_bf16 v[30:33], v[98:101], v[110:113], v[22:25]
	v_ashrrev_i32_e32 v77, 31, v76
	v_cmp_lt_i32_e32 vcc, s62, v76
	s_and_b64 s[38:39], s[44:45], vcc
	v_mfma_f32_16x16x32_bf16 v[22:25], v[102:105], v[110:113], v[14:17]
	v_cmp_gt_i32_e64 s[12:13], s57, v74
	s_nor_b64 s[8:9], s[12:13], s[38:39]
	s_nop 0
	v_mad_i64_i32 v[14:15], s[4:5], v74, s58, v[172:173]
	v_lshl_add_u64 v[78:79], v[76:77], 1, v[14:15]
	v_mfma_f32_16x16x32_bf16 v[18:21], v[106:109], v[110:113], v[10:13]
	v_cmp_gt_i32_e64 s[4:5], s61, v76
	s_nop 1
	v_cvt_pk_bf16_f32 v10, v62, v63
	v_cvt_pk_bf16_f32 v11, v64, v65
	global_store_dwordx2 v[78:79], v[10:11], off
	v_mfma_f32_16x16x32_bf16 v[10:13], v[82:85], v[114:117], v[2:5]
	s_nop 2
	v_add_u32_e32 v2, 0xffffe000, v74
	v_mfma_f32_16x16x32_bf16 v[14:17], v[98:101], v[114:117], v[6:9]
	v_lshrrev_b32_e32 v82, 2, v2
	v_mfma_f32_16x16x32_bf16 v[6:9], v[102:105], v[114:117], v[94:97]
	v_mfma_f32_16x16x32_bf16 v[2:5], v[106:109], v[114:117], v[90:93]
	s_and_saveexec_b64 s[6:7], s[8:9]
	s_cbranch_execz .LBB0_234
	v_and_b32_e32 v74, 3, v80
	s_and_saveexec_b64 s[8:9], s[4:5]
	s_xor_b64 s[8:9], exec, s[8:9]
	s_cbranch_execz .LBB0_232
	v_cmp_ne_u32_e32 vcc, 0, v74
	s_and_saveexec_b64 s[10:11], vcc
	s_cbranch_execz .LBB0_231
	v_lshl_add_u32 v83, v82, 1, v82
	v_add3_u32 v74, v74, v83, -1
	v_mov_b64_e32 v[84:85], s[22:23]
	v_mad_u64_u32 v[84:85], s[40:41], v74, s58, v[84:85]
	v_lshl_add_u64 v[84:85], v[76:77], 2, v[84:85]
	global_store_dwordx4 v[84:85], v[62:65], off
